# FoX loop: fragment + gate LDS reads issued before next-tile loads
# baseline (speedup 1.0000x reference)
; #define LAS __attribute__((address_space(3)))
; __device__ __forceinline__ s16x4 tr_read(LAS const unsigned char* p) { return __builtin_bit_cast(s16x4, __builtin_amdgcn_ds_read_tr16_b64_v4i16((LAS s16x4*)p)); }
; __device__ __forceinline__ s16x8 cat8(s16x4 a, s16x4 b) { return (s16x8){a[0], a[1], a[2], a[3], b[0], b[1], b[2], b[3]}; }
; #define MFMA32(a, b, c) __builtin_amdgcn_mfma_f32_32x32x16_bf16(a, b, c, 0, 0, 0)
; __device__ __forceinline__ void attn_mfma_item(const bf16* u, bf16* y, const float* cl, const float* tot, LAS unsigned char* wl, int item, int lane) {
;     ...
;         if (jt > 0) { const char* tb = ubc + (size_t)((jt - 1) * 32) * NU * 2;
; #pragma unroll
;           for (int i = 0; i < 4; ++i) { kn[i] = *(const v4u*)(tb + (size_t)(8 * i * NU + koff) * 2 + lane_off); vn[i] = *(const v4u*)(tb + (size_t)(8 * i * NU + voff) * 2 + lane_off); }
;           if (fox) gn = clh[(jt - 1) * 32 + r]; }
;         s16x8 Kf[4];
; #pragma unroll
;         for (int d0 = 0; d0 < 4; ++d0) Kf[d0] = *(LAS const s16x8*)(kl + kfoff + 32 * d0);
;         LAS const unsigned char* vb = wl + vprev + trbase;
;         const s16x8 V00 = cat8(tr_read(vb), tr_read(vb + 8 * PV64)), V01 = cat8(tr_read(vb + 16 * PV64), tr_read(vb + 24 * PV64));
;         const s16x8 V10 = cat8(tr_read(vb + 64), tr_read(vb + 8 * PV64 + 64)), V11 = cat8(tr_read(vb + 16 * PV64 + 64), tr_read(vb + 24 * PV64 + 64));
;         f32x16 Sx;
; #pragma unroll
;         for (int i = 0; i < 16; ++i) Sx[i] = 0.f;
;         Sx = MFMA32(Kf[0], Qf[0], Sx); O0 = MFMA32(V00, Pp0, O0);
;         Sx = MFMA32(Kf[1], Qf[1], Sx); O1 = MFMA32(V10, Pp0, O1);
;         Sx = MFMA32(Kf[2], Qf[2], Sx); O0 = MFMA32(V01, Pp1, O0);
;         Sx = MFMA32(Kf[3], Qf[3], Sx); O1 = MFMA32(V11, Pp1, O1);
;     ...
;             float kp[16], gs[4], go[4]; float T = 1.f;
; #pragma unroll
;             for (int i = 0; i < 16; ++i) { const float ee = __builtin_amdgcn_exp2f(Sx[i]); const float sig = __builtin_amdgcn_rcpf(1.0f + ee); P[i] = sig; kp[i] = 1.0f - sig; }
;             if (diag) {
; #pragma unroll
;                 for (int i = 0; i < 16; ++i) { const int sl = 8 * (i >> 2) + 4 * hi + (i & 3); if (sl >= r) { P[i] = 0.f; kp[i] = 1.f; } } }
.LBB0_752:
	ds_read_b128 v[234:237], v188 offset:4704
	ds_read_b128 v[238:241], v188 offset:4672
	ds_read_b128 v[242:245], v188 offset:4640
	ds_read_b128 v[246:249], v188 offset:4608
	v_add_u32_e32 v1, v190, v187
	ds_read_b128 v[36:39], v1 offset:4736
	ds_read_b128 v[56:59], v1 offset:4768
	v_subrev_u32_e32 v2, s33, v189
	ds_read_b64_tr_b16 v[60:61], v2 offset:9344
	ds_read_b64_tr_b16 v[62:63], v2 offset:10496
	ds_read_b64_tr_b16 v[66:67], v2 offset:10560
	ds_read_b64_tr_b16 v[64:65], v2 offset:9408
	s_cmp_lg_u32 s1, 0
	s_cselect_b64 s[86:87], -1, 0
	s_cmp_eq_u32 s1, 0
	s_cbranch_scc1 .LBB0_755
	v_mad_u64_u32 v[226:227], s[70:71], s83, v215, v[122:123]
	v_lshl_add_u64 v[228:229], v[226:227], 0, s[54:55]
	v_lshl_add_u64 v[230:231], v[226:227], 0, s[56:57]
	global_load_dwordx4 v[84:87], v[228:229], off
	global_load_dwordx4 v[88:91], v[230:231], off
	v_lshl_add_u64 v[228:229], v[226:227], 0, s[58:59]
	v_lshl_add_u64 v[230:231], v[226:227], 0, s[60:61]
	global_load_dwordx4 v[92:95], v[228:229], off
	global_load_dwordx4 v[96:99], v[230:231], off
	v_lshl_add_u64 v[228:229], v[226:227], 0, s[62:63]
	v_lshl_add_u64 v[230:231], v[226:227], 0, s[64:65]
	global_load_dwordx4 v[100:103], v[228:229], off
	global_load_dwordx4 v[104:107], v[230:231], off
	v_lshl_add_u64 v[228:229], v[226:227], 0, s[66:67]
	v_lshl_add_u64 v[226:227], v[226:227], 0, s[68:69]
	global_load_dwordx4 v[108:111], v[228:229], off
	global_load_dwordx4 v[112:115], v[226:227], off
	s_and_b64 vcc, exec, s[92:93]
	s_cbranch_vccnz .LBB0_755
	v_add_u32_e32 v232, s83, v145
	v_lshlrev_b32_e32 v232, 2, v232
	global_load_dword v135, v232, s[52:53]
.LBB0_755:
	s_waitcnt lgkmcnt(2)
	v_mfma_f32_32x32x16_bf16 v[20:35], v[60:63], v[52:55], v[20:35]
	s_cmp_eq_u32 s73, 0
	s_cselect_b64 s[94:95], -1, 0
	s_mov_b64 s[70:71], -1
	s_and_b64 vcc, exec, s[50:51]
	v_mfma_f32_32x32x16_bf16 v[36:51], v[36:39], v[68:71], 0
	v_mfma_f32_32x32x16_bf16 v[36:51], v[56:59], v[72:75], v[36:51]
	s_waitcnt lgkmcnt(0)
	v_mfma_f32_32x32x16_bf16 v[4:19], v[64:67], v[52:55], v[4:19]
	ds_read_b128 v[52:55], v1 offset:4800
	ds_read_b128 v[56:59], v1 offset:4832
	v_cndmask_b32_e64 v1, 0, 1, s[94:95]
	v_cmp_ne_u32_e64 s[94:95], 1, v1
	s_waitcnt lgkmcnt(1)
	v_mfma_f32_32x32x16_bf16 v[36:51], v[52:55], v[76:79], v[36:51]
	ds_read_b64_tr_b16 v[52:53], v2 offset:11648
	ds_read_b64_tr_b16 v[54:55], v2 offset:12800
	ds_read_b64_tr_b16 v[126:127], v2 offset:12864
	ds_read_b64_tr_b16 v[124:125], v2 offset:11712
	s_waitcnt lgkmcnt(2)
	v_mfma_f32_32x32x16_bf16 v[20:35], v[52:55], v[116:119], v[20:35]
	v_mfma_f32_32x32x16_bf16 v[36:51], v[56:59], v[80:83], v[36:51]
	s_waitcnt lgkmcnt(0)
	v_mfma_f32_32x32x16_bf16 v[4:19], v[124:127], v[116:119], v[4:19]
	s_cbranch_vccz .LBB0_759
	s_nop 8
	v_exp_f32_e32 v1, v36
	v_exp_f32_e32 v2, v37
	v_exp_f32_e32 v52, v38
	v_exp_f32_e32 v53, v51
	v_add_f32_e32 v1, 1.0, v1
	v_add_f32_e32 v2, 1.0, v2
	v_rcp_f32_e32 v116, v1
	v_rcp_f32_e32 v117, v2
	v_exp_f32_e32 v1, v39
	v_add_f32_e32 v2, 1.0, v52
	v_rcp_f32_e32 v118, v2
	v_exp_f32_e32 v2, v40
	v_add_f32_e32 v1, 1.0, v1
	v_rcp_f32_e32 v119, v1
	v_exp_f32_e32 v1, v41
	v_add_f32_e32 v2, 1.0, v2
	v_rcp_f32_e32 v66, v2
	v_exp_f32_e32 v2, v42
	v_add_f32_e32 v1, 1.0, v1
	v_rcp_f32_e32 v67, v1
	v_exp_f32_e32 v1, v43
	v_add_f32_e32 v2, 1.0, v2
	v_rcp_f32_e32 v124, v2
	v_exp_f32_e32 v2, v44
	v_add_f32_e32 v1, 1.0, v1
	v_rcp_f32_e32 v125, v1
	v_exp_f32_e32 v1, v45
	v_add_f32_e32 v2, 1.0, v2
	v_rcp_f32_e32 v126, v2
	v_exp_f32_e32 v2, v46
	v_exp_f32_e32 v52, v47
	v_add_f32_e32 v1, 1.0, v1
	v_rcp_f32_e32 v127, v1
	v_add_f32_e32 v1, 1.0, v2
	v_rcp_f32_e32 v132, v1
	v_add_f32_e32 v1, 1.0, v52
	v_rcp_f32_e32 v133, v1
	v_exp_f32_e32 v1, v48
	v_exp_f32_e32 v2, v49
	v_exp_f32_e32 v52, v50
	v_add_f32_e32 v53, 1.0, v53
	v_add_f32_e32 v1, 1.0, v1
	v_add_f32_e32 v2, 1.0, v2
	v_add_f32_e32 v52, 1.0, v52
	v_rcp_f32_e32 v131, v53
	v_rcp_f32_e32 v130, v52
	v_rcp_f32_e32 v129, v2
	v_rcp_f32_e32 v128, v1
	v_sub_f32_e32 v63, 1.0, v131
	v_sub_f32_e32 v56, 1.0, v130
	v_sub_f32_e32 v61, 1.0, v129
	v_sub_f32_e32 v58, 1.0, v128
	v_sub_f32_e32 v59, 1.0, v133
	v_sub_f32_e32 v54, 1.0, v132
	v_sub_f32_e32 v57, 1.0, v127
	v_sub_f32_e32 v60, 1.0, v126
	v_sub_f32_e32 v55, 1.0, v125
	v_sub_f32_e32 v52, 1.0, v124
	v_sub_f32_e32 v65, 1.0, v67
	v_sub_f32_e32 v62, 1.0, v66
	v_sub_f32_e32 v53, 1.0, v119
	v_sub_f32_e32 v2, 1.0, v118
	s_and_b64 vcc, exec, s[94:95]
	v_sub_f32_e32 v1, 1.0, v117
	v_sub_f32_e32 v64, 1.0, v116
	s_cbranch_vccnz .LBB0_758
	v_readlane_b32 s34, v254, 28
	v_readlane_b32 s70, v254, 0
	v_readlane_b32 s96, v254, 2
	v_readlane_b32 s48, v254, 4
	v_readlane_b32 s90, v254, 6
	v_readlane_b32 s88, v254, 8
	v_readlane_b32 s80, v254, 10
	v_readlane_b32 s16, v254, 12
	v_readlane_b32 s76, v254, 14
	v_readlane_b32 s78, v254, 16
	v_readlane_b32 s74, v254, 18
	v_readlane_b32 s42, v254, 20
	v_readlane_b32 s40, v254, 22
	v_readlane_b32 s38, v254, 24
	v_readlane_b32 s36, v254, 26
	v_readlane_b32 s35, v254, 29
	v_readlane_b32 s71, v254, 1
	v_readlane_b32 s97, v254, 3
	v_readlane_b32 s49, v254, 5
	v_readlane_b32 s91, v254, 7
	v_readlane_b32 s89, v254, 9
	v_readlane_b32 s81, v254, 11
	v_readlane_b32 s17, v254, 13
	v_readlane_b32 s77, v254, 15
	v_readlane_b32 s79, v254, 17
	v_readlane_b32 s75, v254, 19
	v_readlane_b32 s43, v254, 21
	v_readlane_b32 s41, v254, 23
	v_readlane_b32 s39, v254, 25
	v_readlane_b32 s37, v254, 27
	s_or_b64 vcc, s[34:35], s[18:19]
	v_cndmask_b32_e64 v63, 1.0, v63, s[70:71]
	v_cndmask_b32_e64 v56, 1.0, v56, s[96:97]
	v_cndmask_b32_e64 v61, 1.0, v61, s[48:49]
	v_cndmask_b32_e64 v58, 1.0, v58, s[90:91]
	v_cndmask_b32_e64 v59, 1.0, v59, s[88:89]
	v_cndmask_b32_e64 v54, 1.0, v54, s[80:81]
	v_cndmask_b32_e64 v57, 1.0, v57, s[16:17]
	v_cndmask_b32_e64 v60, 1.0, v60, s[76:77]
	v_cndmask_b32_e64 v55, 1.0, v55, s[78:79]
	v_cndmask_b32_e64 v52, 1.0, v52, s[74:75]
	v_cndmask_b32_e64 v65, 1.0, v65, s[42:43]
	v_cndmask_b32_e64 v62, 1.0, v62, s[40:41]
	v_cndmask_b32_e64 v53, 1.0, v53, s[38:39]
	v_cndmask_b32_e64 v2, 1.0, v2, s[36:37]
	v_cndmask_b32_e64 v1, 1.0, v1, s[34:35]
	v_cndmask_b32_e32 v64, 1.0, v64, vcc
	v_cndmask_b32_e64 v131, 0, v131, s[70:71]
	v_cndmask_b32_e64 v130, 0, v130, s[96:97]
	v_cndmask_b32_e64 v129, 0, v129, s[48:49]
	v_cndmask_b32_e64 v128, 0, v128, s[90:91]
	v_cndmask_b32_e64 v133, 0, v133, s[88:89]
	v_cndmask_b32_e64 v132, 0, v132, s[80:81]
	v_cndmask_b32_e64 v127, 0, v127, s[16:17]
	v_cndmask_b32_e64 v126, 0, v126, s[76:77]
	v_cndmask_b32_e64 v125, 0, v125, s[78:79]
	v_cndmask_b32_e64 v124, 0, v124, s[74:75]
	v_cndmask_b32_e64 v67, 0, v67, s[42:43]
	v_cndmask_b32_e64 v66, 0, v66, s[40:41]
	v_cndmask_b32_e64 v119, 0, v119, s[38:39]
	v_cndmask_b32_e64 v118, 0, v118, s[36:37]
	v_cndmask_b32_e64 v117, 0, v117, s[34:35]
	v_cndmask_b32_e32 v116, 0, v116, vcc

; #define LAS __attribute__((address_space(3)))
; __device__ __forceinline__ void attn_mfma_item(const bf16* u, bf16* y, const float* cl, const float* tot, LAS unsigned char* wl, int item, int lane) {
;     ...
;         if (fox) {
;             const float off = clt + Doff;
;             float tmax = -1e30f;
; #pragma unroll
;             for (int g = 0; g < 4; ++g) { const f32x4 ncs = *(LAS const f32x4*)(gl + 8 * g + 4 * hi);
; #pragma unroll
;                 for (int e = 0; e < 4; ++e) P[4 * g + e] = fmaf(SC2, Sx[4 * g + e], ncs[e]); }
;             if (diag) {
; #pragma unroll
;                 for (int i = 0; i < 16; ++i) { const int sl = 8 * (i >> 2) + 4 * hi + (i & 3); if (sl > r) P[i] = -1e30f; } }
.LBB0_759:
	s_and_b64 vcc, exec, s[70:71]
	s_cbranch_vccz .LBB0_768
	s_mov_b32 s70, 0x3e38aa3b
	s_nop 7
	v_pk_fma_f32 v[50:51], v[50:51], s[70:71], v[236:237] op_sel_hi:[1,0,1]
	v_pk_fma_f32 v[46:47], v[46:47], s[70:71], v[240:241] op_sel_hi:[1,0,1]
	v_pk_fma_f32 v[42:43], v[42:43], s[70:71], v[244:245] op_sel_hi:[1,0,1]
	v_pk_fma_f32 v[54:55], v[38:39], s[70:71], v[248:249] op_sel_hi:[1,0,1]
	v_pk_fma_f32 v[38:39], v[48:49], s[70:71], v[234:235] op_sel_hi:[1,0,1]
	v_pk_fma_f32 v[44:45], v[44:45], s[70:71], v[238:239] op_sel_hi:[1,0,1]
	v_pk_fma_f32 v[40:41], v[40:41], s[70:71], v[242:243] op_sel_hi:[1,0,1]
	s_and_b64 vcc, exec, s[94:95]
	v_pk_fma_f32 v[36:37], v[36:37], s[70:71], v[246:247] op_sel_hi:[1,0,1]
	s_cbranch_vccnz .LBB0_762
	v_readlane_b32 s16, v254, 59
	v_readlane_b32 s17, v254, 60
	v_cndmask_b32_e64 v1, v36, v216, s[20:21]
	v_cndmask_b32_e64 v37, v216, v37, s[18:19]
	v_cndmask_b32_e64 v41, v41, v216, s[16:17]
	v_readlane_b32 s16, v254, 57
	v_readlane_b32 s17, v254, 58
	v_cndmask_b32_e64 v36, v1, v36, s[18:19]
	v_cndmask_b32_e64 v54, v54, v216, s[22:23]
	v_cndmask_b32_e64 v42, v42, v216, s[16:17]
	v_readlane_b32 s16, v254, 55
	v_readlane_b32 s17, v254, 56
	v_cndmask_b32_e64 v55, v55, v216, s[24:25]
	v_cndmask_b32_e64 v40, v40, v216, s[26:27]
	v_cndmask_b32_e64 v43, v43, v216, s[16:17]
	v_readlane_b32 s16, v254, 53
	v_readlane_b32 s17, v254, 54
	v_cndmask_b32_e64 v39, v39, v216, s[30:31]
	v_cndmask_b32_e64 v50, v50, v216, s[28:29]
	v_cndmask_b32_e64 v44, v44, v216, s[16:17]
	v_readlane_b32 s16, v254, 51
	v_readlane_b32 s17, v254, 52
	s_nop 1
	v_cndmask_b32_e64 v45, v45, v216, s[16:17]
	v_readlane_b32 s16, v254, 49
	v_readlane_b32 s17, v254, 50
	s_nop 1
	v_cndmask_b32_e64 v46, v46, v216, s[16:17]
	v_readlane_b32 s16, v254, 47
	v_readlane_b32 s17, v254, 48
	s_nop 1
	v_cndmask_b32_e64 v47, v47, v216, s[16:17]
	v_readlane_b32 s16, v254, 45
	v_readlane_b32 s17, v254, 46
	s_nop 1
	v_cndmask_b32_e64 v38, v38, v216, s[16:17]
	v_readlane_b32 s16, v254, 30
	v_readlane_b32 s17, v254, 31
	s_nop 1
	v_cndmask_b32_e64 v51, v51, v216, s[16:17]
